# idle-slot weight conversion loops (FFN1-in, Z, FFN2-in phases): 8 gain loads per item issued together with counted waits instead of 8 serialized round trips
# speedup vs baseline: 1.0091x; 1.0091x over previous
.LBB0_534:
	s_abs_i32 s1, s22
	s_mul_hi_u32 s20, s1, s29
	s_mul_i32 s21, s20, s26
	s_sub_i32 s1, s1, s21
	s_ashr_i32 s0, s22, 31
	s_add_i32 s21, s20, 1
	s_sub_i32 s22, s1, s26
	s_cmp_ge_u32 s1, s26
	s_cselect_b32 s20, s21, s20
	s_cselect_b32 s1, s22, s1
	s_add_i32 s21, s20, 1
	s_cmp_ge_u32 s1, s26
	s_cselect_b32 s1, s21, s20
	s_xor_b32 s1, s1, s0
	s_sub_i32 s42, s1, s0
	s_lshl_b32 s20, s42, 6
	v_or_b32_e32 v68, s20, v70
	v_cndmask_b32_e64 v0, 0, 1, s[16:17]
	v_cmp_ne_u32_e64 s[0:1], 1, v0
	s_andn2_b64 vcc, exec, s[16:17]
	v_ashrrev_i32_e32 v69, 31, v68
	s_cbranch_vccnz .LBB0_562
	v_lshl_add_u64 v[76:77], v[68:69], 2, s[10:11]
	global_load_dword v198, v[76:77], off
	global_load_dword v200, v[76:77], off offset:32
	global_load_dword v202, v[76:77], off offset:64
	global_load_dword v204, v[76:77], off offset:96
	global_load_dword v206, v[76:77], off offset:128
	global_load_dword v208, v[76:77], off offset:160
	global_load_dword v210, v[76:77], off offset:192
	global_load_dword v212, v[76:77], off offset:224
	s_waitcnt vmcnt(7)
	v_pk_mul_f32 v[78:79], v[62:63], v[198:199] op_sel_hi:[1,0]
	ds_write2_b32 v74, v78, v79 offset1:1
	v_pk_mul_f32 v[78:79], v[64:65], v[198:199] op_sel_hi:[1,0]
	ds_write2_b32 v74, v78, v79 offset0:2 offset1:3
	s_waitcnt vmcnt(6)
	v_mov_b32_e32 v0, v200
	s_cbranch_execnz .LBB0_537

.LBB0_537:
	s_waitcnt vmcnt(6)
	v_pk_mul_f32 v[58:59], v[58:59], v[0:1] op_sel_hi:[1,0]
	v_add_u32_e32 v62, 0x420, v74
	ds_write2_b32 v62, v58, v59 offset1:1
	v_pk_mul_f32 v[58:59], v[60:61], v[0:1] op_sel_hi:[1,0]
	v_add_u32_e32 v0, 0x428, v74
	ds_write2_b32 v0, v58, v59 offset1:1
	s_and_b64 vcc, exec, s[0:1]
	v_add_u32_e32 v58, 0x840, v74
	v_add_u32_e32 v59, 0x848, v74
	s_cbranch_vccnz .LBB0_563
	s_waitcnt vmcnt(5)
	v_pk_mul_f32 v[62:63], v[54:55], v[202:203] op_sel_hi:[1,0]
	ds_write2_b32 v58, v62, v63 offset1:1
	v_pk_mul_f32 v[62:63], v[56:57], v[202:203] op_sel_hi:[1,0]
	ds_write2_b32 v59, v62, v63 offset1:1
	s_waitcnt vmcnt(4)
	v_mov_b32_e32 v0, v204
	s_cbranch_execnz .LBB0_540

.LBB0_540:
	s_waitcnt vmcnt(4)
	v_pk_mul_f32 v[50:51], v[50:51], v[0:1] op_sel_hi:[1,0]
	v_add_u32_e32 v54, 0xc60, v74
	ds_write2_b32 v54, v50, v51 offset1:1
	v_pk_mul_f32 v[50:51], v[52:53], v[0:1] op_sel_hi:[1,0]
	v_add_u32_e32 v0, 0xc68, v74
	ds_write2_b32 v0, v50, v51 offset1:1
	s_and_b64 vcc, exec, s[0:1]
	v_add_u32_e32 v50, 0x1080, v74
	v_add_u32_e32 v51, 0x1088, v74
	s_cbranch_vccnz .LBB0_564
	s_waitcnt vmcnt(3)
	v_pk_mul_f32 v[54:55], v[46:47], v[206:207] op_sel_hi:[1,0]
	ds_write2_b32 v50, v54, v55 offset1:1
	v_pk_mul_f32 v[54:55], v[48:49], v[206:207] op_sel_hi:[1,0]
	ds_write2_b32 v51, v54, v55 offset1:1
	s_waitcnt vmcnt(2)
	v_mov_b32_e32 v0, v208
	s_cbranch_execnz .LBB0_543

.LBB0_543:
	s_waitcnt vmcnt(2)
	v_pk_mul_f32 v[42:43], v[42:43], v[0:1] op_sel_hi:[1,0]
	v_add_u32_e32 v46, 0x14a0, v74
	ds_write2_b32 v46, v42, v43 offset1:1
	v_pk_mul_f32 v[42:43], v[44:45], v[0:1] op_sel_hi:[1,0]
	v_add_u32_e32 v0, 0x14a8, v74
	ds_write2_b32 v0, v42, v43 offset1:1
	s_and_b64 vcc, exec, s[0:1]
	v_add_u32_e32 v42, 0x18c0, v74
	v_add_u32_e32 v43, 0x18c8, v74
	s_cbranch_vccnz .LBB0_565
	s_waitcnt vmcnt(1)
	v_pk_mul_f32 v[46:47], v[38:39], v[210:211] op_sel_hi:[1,0]
	ds_write2_b32 v42, v46, v47 offset1:1
	v_pk_mul_f32 v[46:47], v[40:41], v[210:211] op_sel_hi:[1,0]
	ds_write2_b32 v43, v46, v47 offset1:1
	s_waitcnt vmcnt(0)
	v_mov_b32_e32 v0, v212
	s_cbranch_execnz .LBB0_546

.LBB0_690:
	s_abs_i32 s1, s22
	s_mul_hi_u32 s20, s1, s29
	s_mul_i32 s21, s20, s26
	s_sub_i32 s1, s1, s21
	s_ashr_i32 s0, s22, 31
	s_add_i32 s21, s20, 1
	s_sub_i32 s22, s1, s26
	s_cmp_ge_u32 s1, s26
	s_cselect_b32 s20, s21, s20
	s_cselect_b32 s1, s22, s1
	s_add_i32 s21, s20, 1
	s_cmp_ge_u32 s1, s26
	s_cselect_b32 s1, s21, s20
	s_xor_b32 s1, s1, s0
	s_sub_i32 s39, s1, s0
	s_lshl_b32 s20, s39, 6
	v_or_b32_e32 v68, s20, v70
	v_cndmask_b32_e64 v0, 0, 1, s[16:17]
	v_cmp_ne_u32_e64 s[0:1], 1, v0
	s_andn2_b64 vcc, exec, s[16:17]
	v_ashrrev_i32_e32 v69, 31, v68
	s_cbranch_vccnz .LBB0_718
	v_lshl_add_u64 v[74:75], v[68:69], 2, s[10:11]
	global_load_dword v198, v[74:75], off
	global_load_dword v200, v[74:75], off offset:32
	global_load_dword v202, v[74:75], off offset:64
	global_load_dword v204, v[74:75], off offset:96
	global_load_dword v206, v[74:75], off offset:128
	global_load_dword v208, v[74:75], off offset:160
	global_load_dword v210, v[74:75], off offset:192
	global_load_dword v212, v[74:75], off offset:224
	s_waitcnt vmcnt(7)
	v_pk_mul_f32 v[76:77], v[62:63], v[198:199] op_sel_hi:[1,0]
	ds_write2_b32 v73, v76, v77 offset1:1
	v_pk_mul_f32 v[76:77], v[64:65], v[198:199] op_sel_hi:[1,0]
	ds_write2_b32 v73, v76, v77 offset0:2 offset1:3
	s_waitcnt vmcnt(6)
	v_mov_b32_e32 v0, v200
	s_cbranch_execnz .LBB0_693

.LBB0_693:
	s_waitcnt vmcnt(6)
	v_pk_mul_f32 v[58:59], v[58:59], v[0:1] op_sel_hi:[1,0]
	v_add_u32_e32 v62, 0x420, v73
	ds_write2_b32 v62, v58, v59 offset1:1
	v_pk_mul_f32 v[58:59], v[60:61], v[0:1] op_sel_hi:[1,0]
	v_add_u32_e32 v0, 0x428, v73
	ds_write2_b32 v0, v58, v59 offset1:1
	s_and_b64 vcc, exec, s[0:1]
	v_add_u32_e32 v58, 0x840, v73
	v_add_u32_e32 v59, 0x848, v73
	s_cbranch_vccnz .LBB0_719
	s_waitcnt vmcnt(5)
	v_pk_mul_f32 v[62:63], v[54:55], v[202:203] op_sel_hi:[1,0]
	ds_write2_b32 v58, v62, v63 offset1:1
	v_pk_mul_f32 v[62:63], v[56:57], v[202:203] op_sel_hi:[1,0]
	ds_write2_b32 v59, v62, v63 offset1:1
	s_waitcnt vmcnt(4)
	v_mov_b32_e32 v0, v204
	s_cbranch_execnz .LBB0_696

.LBB0_696:
	s_waitcnt vmcnt(4)
	v_pk_mul_f32 v[50:51], v[50:51], v[0:1] op_sel_hi:[1,0]
	v_add_u32_e32 v54, 0xc60, v73
	ds_write2_b32 v54, v50, v51 offset1:1
	v_pk_mul_f32 v[50:51], v[52:53], v[0:1] op_sel_hi:[1,0]
	v_add_u32_e32 v0, 0xc68, v73
	ds_write2_b32 v0, v50, v51 offset1:1
	s_and_b64 vcc, exec, s[0:1]
	v_add_u32_e32 v50, 0x1080, v73
	v_add_u32_e32 v51, 0x1088, v73
	s_cbranch_vccnz .LBB0_720
	s_waitcnt vmcnt(3)
	v_pk_mul_f32 v[54:55], v[46:47], v[206:207] op_sel_hi:[1,0]
	ds_write2_b32 v50, v54, v55 offset1:1
	v_pk_mul_f32 v[54:55], v[48:49], v[206:207] op_sel_hi:[1,0]
	ds_write2_b32 v51, v54, v55 offset1:1
	s_waitcnt vmcnt(2)
	v_mov_b32_e32 v0, v208
	s_cbranch_execnz .LBB0_699

.LBB0_699:
	s_waitcnt vmcnt(2)
	v_pk_mul_f32 v[42:43], v[42:43], v[0:1] op_sel_hi:[1,0]
	v_add_u32_e32 v46, 0x14a0, v73
	ds_write2_b32 v46, v42, v43 offset1:1
	v_pk_mul_f32 v[42:43], v[44:45], v[0:1] op_sel_hi:[1,0]
	v_add_u32_e32 v0, 0x14a8, v73
	ds_write2_b32 v0, v42, v43 offset1:1
	s_and_b64 vcc, exec, s[0:1]
	v_add_u32_e32 v42, 0x18c0, v73
	v_add_u32_e32 v43, 0x18c8, v73
	s_cbranch_vccnz .LBB0_721
	s_waitcnt vmcnt(1)
	v_pk_mul_f32 v[46:47], v[38:39], v[210:211] op_sel_hi:[1,0]
	ds_write2_b32 v42, v46, v47 offset1:1
	v_pk_mul_f32 v[46:47], v[40:41], v[210:211] op_sel_hi:[1,0]
	ds_write2_b32 v43, v46, v47 offset1:1
	s_waitcnt vmcnt(0)
	v_mov_b32_e32 v0, v212
	s_cbranch_execnz .LBB0_702

.LBB0_1429:
	s_abs_i32 s1, s22
	s_mul_hi_u32 s20, s1, s28
	s_mul_i32 s21, s20, s25
	s_sub_i32 s1, s1, s21
	s_ashr_i32 s0, s22, 31
	s_add_i32 s21, s20, 1
	s_sub_i32 s22, s1, s25
	s_cmp_ge_u32 s1, s25
	s_cselect_b32 s20, s21, s20
	s_cselect_b32 s1, s22, s1
	s_add_i32 s21, s20, 1
	s_cmp_ge_u32 s1, s25
	s_cselect_b32 s1, s21, s20
	s_xor_b32 s1, s1, s0
	s_sub_i32 s38, s1, s0
	s_lshl_b32 s20, s38, 6
	v_or_b32_e32 v68, s20, v70
	v_cndmask_b32_e64 v0, 0, 1, s[16:17]
	v_cmp_ne_u32_e64 s[0:1], 1, v0
	s_andn2_b64 vcc, exec, s[16:17]
	v_ashrrev_i32_e32 v69, 31, v68
	s_cbranch_vccnz .LBB0_1457
	v_lshl_add_u64 v[74:75], v[68:69], 2, s[10:11]
	global_load_dword v198, v[74:75], off
	global_load_dword v200, v[74:75], off offset:32
	global_load_dword v202, v[74:75], off offset:64
	global_load_dword v204, v[74:75], off offset:96
	global_load_dword v206, v[74:75], off offset:128
	global_load_dword v208, v[74:75], off offset:160
	global_load_dword v210, v[74:75], off offset:192
	global_load_dword v212, v[74:75], off offset:224
	s_waitcnt vmcnt(7)
	v_pk_mul_f32 v[76:77], v[62:63], v[198:199] op_sel_hi:[1,0]
	ds_write2_b32 v73, v76, v77 offset1:1
	v_pk_mul_f32 v[76:77], v[64:65], v[198:199] op_sel_hi:[1,0]
	ds_write2_b32 v73, v76, v77 offset0:2 offset1:3
	s_waitcnt vmcnt(6)
	v_mov_b32_e32 v0, v200
	s_cbranch_execnz .LBB0_1432

.LBB0_2207:
	s_abs_i32 s3, s22
	s_mul_hi_u32 s20, s3, s29
	s_mul_i32 s21, s20, s26
	s_sub_i32 s3, s3, s21
	s_ashr_i32 s2, s22, 31
	s_add_i32 s21, s20, 1
	s_sub_i32 s22, s3, s26
	s_cmp_ge_u32 s3, s26
	s_cselect_b32 s20, s21, s20
	s_cselect_b32 s3, s22, s3
	s_add_i32 s21, s20, 1
	s_cmp_ge_u32 s3, s26
	s_cselect_b32 s3, s21, s20
	s_xor_b32 s3, s3, s2
	s_sub_i32 s42, s3, s2
	s_lshl_b32 s20, s42, 6
	v_or_b32_e32 v68, s20, v70
	v_cndmask_b32_e64 v0, 0, 1, s[16:17]
	v_cmp_ne_u32_e64 s[2:3], 1, v0
	s_andn2_b64 vcc, exec, s[16:17]
	v_ashrrev_i32_e32 v69, 31, v68
	s_cbranch_vccnz .LBB0_2235
	v_lshl_add_u64 v[76:77], v[68:69], 2, s[12:13]
	global_load_dword v198, v[76:77], off
	global_load_dword v200, v[76:77], off offset:32
	global_load_dword v202, v[76:77], off offset:64
	global_load_dword v204, v[76:77], off offset:96
	global_load_dword v206, v[76:77], off offset:128
	global_load_dword v208, v[76:77], off offset:160
	global_load_dword v210, v[76:77], off offset:192
	global_load_dword v212, v[76:77], off offset:224
	s_waitcnt vmcnt(7)
	v_pk_mul_f32 v[78:79], v[62:63], v[198:199] op_sel_hi:[1,0]
	ds_write2_b32 v74, v78, v79 offset1:1
	v_pk_mul_f32 v[78:79], v[64:65], v[198:199] op_sel_hi:[1,0]
	ds_write2_b32 v74, v78, v79 offset0:2 offset1:3
	s_waitcnt vmcnt(6)
	v_mov_b32_e32 v0, v200
	s_cbranch_execnz .LBB0_2210

.LBB0_2210:
	s_waitcnt vmcnt(6)
	v_pk_mul_f32 v[58:59], v[58:59], v[0:1] op_sel_hi:[1,0]
	v_add_u32_e32 v62, 0x420, v74
	ds_write2_b32 v62, v58, v59 offset1:1
	v_pk_mul_f32 v[58:59], v[60:61], v[0:1] op_sel_hi:[1,0]
	v_add_u32_e32 v0, 0x428, v74
	ds_write2_b32 v0, v58, v59 offset1:1
	s_and_b64 vcc, exec, s[2:3]
	v_add_u32_e32 v58, 0x840, v74
	v_add_u32_e32 v59, 0x848, v74
	s_cbranch_vccnz .LBB0_2236
	s_waitcnt vmcnt(5)
	v_pk_mul_f32 v[62:63], v[54:55], v[202:203] op_sel_hi:[1,0]
	ds_write2_b32 v58, v62, v63 offset1:1
	v_pk_mul_f32 v[62:63], v[56:57], v[202:203] op_sel_hi:[1,0]
	ds_write2_b32 v59, v62, v63 offset1:1
	s_waitcnt vmcnt(4)
	v_mov_b32_e32 v0, v204
	s_cbranch_execnz .LBB0_2213

.LBB0_2213:
	s_waitcnt vmcnt(4)
	v_pk_mul_f32 v[50:51], v[50:51], v[0:1] op_sel_hi:[1,0]
	v_add_u32_e32 v54, 0xc60, v74
	ds_write2_b32 v54, v50, v51 offset1:1
	v_pk_mul_f32 v[50:51], v[52:53], v[0:1] op_sel_hi:[1,0]
	v_add_u32_e32 v0, 0xc68, v74
	ds_write2_b32 v0, v50, v51 offset1:1
	s_and_b64 vcc, exec, s[2:3]
	v_add_u32_e32 v50, 0x1080, v74
	v_add_u32_e32 v51, 0x1088, v74
	s_cbranch_vccnz .LBB0_2237
	s_waitcnt vmcnt(3)
	v_pk_mul_f32 v[54:55], v[46:47], v[206:207] op_sel_hi:[1,0]
	ds_write2_b32 v50, v54, v55 offset1:1
	v_pk_mul_f32 v[54:55], v[48:49], v[206:207] op_sel_hi:[1,0]
	ds_write2_b32 v51, v54, v55 offset1:1
	s_waitcnt vmcnt(2)
	v_mov_b32_e32 v0, v208
	s_cbranch_execnz .LBB0_2216

.LBB0_2216:
	s_waitcnt vmcnt(2)
	v_pk_mul_f32 v[42:43], v[42:43], v[0:1] op_sel_hi:[1,0]
	v_add_u32_e32 v46, 0x14a0, v74
	ds_write2_b32 v46, v42, v43 offset1:1
	v_pk_mul_f32 v[42:43], v[44:45], v[0:1] op_sel_hi:[1,0]
	v_add_u32_e32 v0, 0x14a8, v74
	ds_write2_b32 v0, v42, v43 offset1:1
	s_and_b64 vcc, exec, s[2:3]
	v_add_u32_e32 v42, 0x18c0, v74
	v_add_u32_e32 v43, 0x18c8, v74
	s_cbranch_vccnz .LBB0_2238
	s_waitcnt vmcnt(1)
	v_pk_mul_f32 v[46:47], v[38:39], v[210:211] op_sel_hi:[1,0]
	ds_write2_b32 v42, v46, v47 offset1:1
	v_pk_mul_f32 v[46:47], v[40:41], v[210:211] op_sel_hi:[1,0]
	ds_write2_b32 v43, v46, v47 offset1:1
	s_waitcnt vmcnt(0)
	v_mov_b32_e32 v0, v212
	s_cbranch_execnz .LBB0_2219

.LBB0_2363:
	s_abs_i32 s3, s22
	s_mul_hi_u32 s20, s3, s29
	s_mul_i32 s21, s20, s26
	s_sub_i32 s3, s3, s21
	s_ashr_i32 s2, s22, 31
	s_add_i32 s21, s20, 1
	s_sub_i32 s22, s3, s26
	s_cmp_ge_u32 s3, s26
	s_cselect_b32 s20, s21, s20
	s_cselect_b32 s3, s22, s3
	s_add_i32 s21, s20, 1
	s_cmp_ge_u32 s3, s26
	s_cselect_b32 s3, s21, s20
	s_xor_b32 s3, s3, s2
	s_sub_i32 s39, s3, s2
	s_lshl_b32 s20, s39, 6
	v_or_b32_e32 v68, s20, v70
	v_cndmask_b32_e64 v0, 0, 1, s[16:17]
	v_cmp_ne_u32_e64 s[2:3], 1, v0
	s_andn2_b64 vcc, exec, s[16:17]
	v_ashrrev_i32_e32 v69, 31, v68
	s_cbranch_vccnz .LBB0_2391
	v_lshl_add_u64 v[74:75], v[68:69], 2, s[12:13]
	global_load_dword v198, v[74:75], off
	global_load_dword v200, v[74:75], off offset:32
	global_load_dword v202, v[74:75], off offset:64
	global_load_dword v204, v[74:75], off offset:96
	global_load_dword v206, v[74:75], off offset:128
	global_load_dword v208, v[74:75], off offset:160
	global_load_dword v210, v[74:75], off offset:192
	global_load_dword v212, v[74:75], off offset:224
	s_waitcnt vmcnt(7)
	v_pk_mul_f32 v[76:77], v[62:63], v[198:199] op_sel_hi:[1,0]
	ds_write2_b32 v73, v76, v77 offset1:1
	v_pk_mul_f32 v[76:77], v[64:65], v[198:199] op_sel_hi:[1,0]
	ds_write2_b32 v73, v76, v77 offset0:2 offset1:3
	s_waitcnt vmcnt(6)
	v_mov_b32_e32 v0, v200
	s_cbranch_execnz .LBB0_2366

.LBB0_2366:
	s_waitcnt vmcnt(6)
	v_pk_mul_f32 v[58:59], v[58:59], v[0:1] op_sel_hi:[1,0]
	v_add_u32_e32 v62, 0x420, v73
	ds_write2_b32 v62, v58, v59 offset1:1
	v_pk_mul_f32 v[58:59], v[60:61], v[0:1] op_sel_hi:[1,0]
	v_add_u32_e32 v0, 0x428, v73
	ds_write2_b32 v0, v58, v59 offset1:1
	s_and_b64 vcc, exec, s[2:3]
	v_add_u32_e32 v58, 0x840, v73
	v_add_u32_e32 v59, 0x848, v73
	s_cbranch_vccnz .LBB0_2392
	s_waitcnt vmcnt(5)
	v_pk_mul_f32 v[62:63], v[54:55], v[202:203] op_sel_hi:[1,0]
	ds_write2_b32 v58, v62, v63 offset1:1
	v_pk_mul_f32 v[62:63], v[56:57], v[202:203] op_sel_hi:[1,0]
	ds_write2_b32 v59, v62, v63 offset1:1
	s_waitcnt vmcnt(4)
	v_mov_b32_e32 v0, v204
	s_cbranch_execnz .LBB0_2369

.LBB0_2369:
	s_waitcnt vmcnt(4)
	v_pk_mul_f32 v[50:51], v[50:51], v[0:1] op_sel_hi:[1,0]
	v_add_u32_e32 v54, 0xc60, v73
	ds_write2_b32 v54, v50, v51 offset1:1
	v_pk_mul_f32 v[50:51], v[52:53], v[0:1] op_sel_hi:[1,0]
	v_add_u32_e32 v0, 0xc68, v73
	ds_write2_b32 v0, v50, v51 offset1:1
	s_and_b64 vcc, exec, s[2:3]
	v_add_u32_e32 v50, 0x1080, v73
	v_add_u32_e32 v51, 0x1088, v73
	s_cbranch_vccnz .LBB0_2393
	s_waitcnt vmcnt(3)
	v_pk_mul_f32 v[54:55], v[46:47], v[206:207] op_sel_hi:[1,0]
	ds_write2_b32 v50, v54, v55 offset1:1
	v_pk_mul_f32 v[54:55], v[48:49], v[206:207] op_sel_hi:[1,0]
	ds_write2_b32 v51, v54, v55 offset1:1
	s_waitcnt vmcnt(2)
	v_mov_b32_e32 v0, v208
	s_cbranch_execnz .LBB0_2372

.LBB0_2372:
	s_waitcnt vmcnt(2)
	v_pk_mul_f32 v[42:43], v[42:43], v[0:1] op_sel_hi:[1,0]
	v_add_u32_e32 v46, 0x14a0, v73
	ds_write2_b32 v46, v42, v43 offset1:1
	v_pk_mul_f32 v[42:43], v[44:45], v[0:1] op_sel_hi:[1,0]
	v_add_u32_e32 v0, 0x14a8, v73
	ds_write2_b32 v0, v42, v43 offset1:1
	s_and_b64 vcc, exec, s[2:3]
	v_add_u32_e32 v42, 0x18c0, v73
	v_add_u32_e32 v43, 0x18c8, v73
	s_cbranch_vccnz .LBB0_2394
	s_waitcnt vmcnt(1)
	v_pk_mul_f32 v[46:47], v[38:39], v[210:211] op_sel_hi:[1,0]
	ds_write2_b32 v42, v46, v47 offset1:1
	v_pk_mul_f32 v[46:47], v[40:41], v[210:211] op_sel_hi:[1,0]
	ds_write2_b32 v43, v46, v47 offset1:1
	s_waitcnt vmcnt(0)
	v_mov_b32_e32 v0, v212
	s_cbranch_execnz .LBB0_2375
